# P4 epilogue: out stores with default (write-back, L2-combined) policy instead of nt; plus x loads nt
# baseline (speedup 1.0000x reference)
.LBB0_477:
	v_mov_b32_e32 v144, v254
	s_lshl_b32 s21, s26, 8
	v_readfirstlane_b32 s19, v144
	s_ashr_i32 s26, s19, 2
	s_andn2_b32 s26, s26, 63
	s_add_i32 s26, s26, s21
	v_and_or_b32 v142, v144, 15, s26
	v_ashrrev_i32_e32 v143, 31, v142
	v_lshlrev_b64 v[140:141], 6, v[142:143]
	v_lshl_add_u64 v[140:141], s[6:7], 0, v[140:141]
	global_load_dwordx4 v[152:155], v[140:141], off
	global_load_dwordx4 v[156:159], v[140:141], off offset:16
	global_load_dwordx4 v[160:163], v[140:141], off offset:48
	global_load_dwordx4 v[164:167], v[140:141], off offset:32
	s_lshl_b32 s21, s49, 8
	s_and_b32 s19, s19, 0xc0
	v_lshrrev_b32_e32 v144, 1, v144
	s_or_b32 s19, s19, s21
	v_and_or_b32 v140, v144, 24, s19
	v_ashrrev_i32_e32 v141, 31, v140
	v_lshlrev_b64 v[144:145], 10, v[142:143]
	v_lshl_add_u64 v[144:145], v[144:145], 0, v[140:141]
	v_lshlrev_b64 v[172:173], 1, v[144:145]
	v_lshl_add_u64 v[176:177], s[16:17], 0, v[172:173]
	v_lshl_add_u64 v[178:179], s[14:15], 0, v[172:173]
	global_load_dwordx4 v[168:171], v[176:177], off
	global_load_dwordx4 v[172:175], v[178:179], off
	v_lshl_add_u64 v[144:145], v[144:145], 2, s[30:31]
	s_waitcnt vmcnt(0)
	v_mov_b32_e32 v180, v153
	v_mov_b32_e32 v181, v154
	v_mov_b32_e32 v153, v155
	v_mov_b32_e32 v154, v157
	v_mov_b32_e32 v155, v158
	v_mov_b32_e32 v157, v159
	v_pk_add_f32 v[152:153], v[180:181], v[152:153]
	v_pk_add_f32 v[154:155], v[154:155], v[156:157]
	v_pk_add_f32 v[152:153], v[152:153], v[152:153] op_sel:[0,1] op_sel_hi:[1,0]
	v_pk_add_f32 v[154:155], v[154:155], v[154:155] op_sel:[0,1] op_sel_hi:[1,0]
	v_add_f32_e32 v158, v164, v165
	v_add_f32_e32 v164, v166, v167
	v_mov_b32_e32 v159, v162
	v_mov_b32_e32 v165, v163
	v_mov_b32_e32 v153, v160
	v_mov_b32_e32 v155, v161
	v_pk_add_f32 v[156:157], v[158:159], v[164:165]
	v_pk_add_f32 v[152:153], v[152:153], v[154:155]
	v_lshlrev_b32_e32 v158, 16, v168
	v_pk_add_f32 v[152:153], v[152:153], v[156:157]
	v_and_b32_e32 v159, 0xffff0000, v168
	v_add_f32_e32 v143, v152, v153
	v_fmamk_f32 v143, v143, 0x3a800000, v150
	v_mul_f32_e32 v151, 0x4b800000, v143
	v_cmp_gt_f32_e32 vcc, s48, v143
	v_lshlrev_b32_e32 v162, 16, v172
	v_and_b32_e32 v163, 0xffff0000, v172
	v_cndmask_b32_e32 v143, v143, v151, vcc
	v_rsq_f32_e32 v143, v143
	v_lshlrev_b32_e32 v164, 16, v169
	v_and_b32_e32 v165, 0xffff0000, v169
	v_lshlrev_b32_e32 v166, 16, v173
	v_mul_f32_e32 v151, 0x45800000, v143
	v_cndmask_b32_e32 v154, v143, v151, vcc
	v_pk_mul_f32 v[126:127], v[126:127], v[154:155] op_sel_hi:[1,0]
	v_pk_mul_f32 v[124:125], v[124:125], v[154:155] op_sel_hi:[1,0]
	v_pk_mul_f32 v[122:123], v[122:123], v[154:155] op_sel_hi:[1,0]
	v_pk_mul_f32 v[120:121], v[120:121], v[154:155] op_sel_hi:[1,0]
	v_mul_f32_e32 v124, 0xbfb8aa3b, v124
	v_mul_f32_e32 v125, 0xbfb8aa3b, v125
	v_mul_f32_e32 v126, 0xbfb8aa3b, v126
	v_mul_f32_e32 v127, 0xbfb8aa3b, v127
	v_mul_f32_e32 v120, 0xbfb8aa3b, v120
	v_mul_f32_e32 v121, 0xbfb8aa3b, v121
	v_mul_f32_e32 v122, 0xbfb8aa3b, v122
	v_mul_f32_e32 v123, 0xbfb8aa3b, v123
	v_exp_f32_e32 v124, v124
	v_exp_f32_e32 v125, v125
	v_exp_f32_e32 v126, v126
	v_exp_f32_e32 v127, v127
	v_exp_f32_e32 v120, v120
	v_exp_f32_e32 v121, v121
	v_exp_f32_e32 v122, v122
	v_exp_f32_e32 v123, v123
	v_add_f32_e32 v124, 1.0, v124
	v_add_f32_e32 v125, 1.0, v125
	v_add_f32_e32 v126, 1.0, v126
	v_add_f32_e32 v127, 1.0, v127
	v_add_f32_e32 v143, 1.0, v120
	v_add_f32_e32 v151, 1.0, v121
	v_add_f32_e32 v155, 1.0, v122
	v_add_f32_e32 v156, 1.0, v123
	v_rcp_f32_e32 v120, v124
	v_rcp_f32_e32 v121, v125
	v_rcp_f32_e32 v122, v126
	v_rcp_f32_e32 v123, v127
	v_rcp_f32_e32 v124, v143
	v_rcp_f32_e32 v125, v151
	v_rcp_f32_e32 v126, v155
	v_rcp_f32_e32 v127, v156
	v_and_b32_e32 v167, 0xffff0000, v173
	v_lshlrev_b32_e32 v168, 16, v170
	v_and_b32_e32 v169, 0xffff0000, v170
	v_lshlrev_b32_e32 v172, 16, v174
	v_and_b32_e32 v173, 0xffff0000, v174
	v_lshlrev_b32_e32 v170, 16, v171
	v_and_b32_e32 v171, 0xffff0000, v171
	v_lshlrev_b32_e32 v152, 16, v175
	v_and_b32_e32 v153, 0xffff0000, v175
	v_pk_fma_f32 v[120:121], v[120:121], v[162:163], v[158:159]
	v_pk_fma_f32 v[122:123], v[122:123], v[166:167], v[164:165]
	v_pk_fma_f32 v[124:125], v[124:125], v[172:173], v[168:169]
	v_pk_fma_f32 v[126:127], v[126:127], v[152:153], v[170:171]
	global_store_dwordx4 v[144:145], v[120:123], off
	global_store_dwordx4 v[144:145], v[124:127], off offset:16
	global_load_dwordx4 v[120:123], v[176:177], off offset:64
	s_nop 0
	global_load_dwordx4 v[124:127], v[178:179], off offset:64
	v_pk_mul_f32 v[118:119], v[118:119], v[154:155] op_sel_hi:[1,0]
	v_pk_mul_f32 v[116:117], v[116:117], v[154:155] op_sel_hi:[1,0]
	v_pk_mul_f32 v[114:115], v[114:115], v[154:155] op_sel_hi:[1,0]
	v_pk_mul_f32 v[112:113], v[112:113], v[154:155] op_sel_hi:[1,0]
	v_mul_f32_e32 v116, 0xbfb8aa3b, v116
	v_mul_f32_e32 v117, 0xbfb8aa3b, v117
	v_mul_f32_e32 v118, 0xbfb8aa3b, v118
	v_mul_f32_e32 v119, 0xbfb8aa3b, v119
	v_mul_f32_e32 v112, 0xbfb8aa3b, v112
	v_mul_f32_e32 v113, 0xbfb8aa3b, v113
	v_mul_f32_e32 v114, 0xbfb8aa3b, v114
	v_mul_f32_e32 v115, 0xbfb8aa3b, v115
	v_exp_f32_e32 v116, v116
	v_exp_f32_e32 v117, v117
	v_exp_f32_e32 v118, v118
	v_exp_f32_e32 v119, v119
	v_exp_f32_e32 v112, v112
	v_exp_f32_e32 v113, v113
	v_exp_f32_e32 v114, v114
	v_exp_f32_e32 v115, v115
	v_add_f32_e32 v116, 1.0, v116
	v_add_f32_e32 v117, 1.0, v117
	v_add_f32_e32 v118, 1.0, v118
	v_add_f32_e32 v119, 1.0, v119
	v_add_f32_e32 v143, 1.0, v112
	v_add_f32_e32 v151, 1.0, v113
	v_add_f32_e32 v154, 1.0, v114
	v_add_f32_e32 v155, 1.0, v115
	v_rcp_f32_e32 v112, v116
	v_rcp_f32_e32 v113, v117
	v_rcp_f32_e32 v114, v118
	v_rcp_f32_e32 v115, v119
	v_rcp_f32_e32 v116, v143
	v_rcp_f32_e32 v117, v151
	v_rcp_f32_e32 v118, v154
	v_rcp_f32_e32 v119, v155
	v_or_b32_e32 v152, 16, v142
	v_ashrrev_i32_e32 v153, 31, v152
	v_lshlrev_b64 v[156:157], 6, v[152:153]
	v_lshl_add_u64 v[156:157], s[6:7], 0, v[156:157]
	s_waitcnt vmcnt(1)
	v_lshlrev_b32_e32 v154, 16, v120
	v_and_b32_e32 v155, 0xffff0000, v120
	s_waitcnt vmcnt(0)
	v_lshlrev_b32_e32 v158, 16, v124
	v_and_b32_e32 v159, 0xffff0000, v124
	v_lshlrev_b32_e32 v120, 16, v121
	v_and_b32_e32 v121, 0xffff0000, v121
	v_lshlrev_b32_e32 v124, 16, v125
	v_and_b32_e32 v125, 0xffff0000, v125
	v_lshlrev_b32_e32 v160, 16, v122
	v_and_b32_e32 v161, 0xffff0000, v122
	v_lshlrev_b32_e32 v162, 16, v126
	v_and_b32_e32 v163, 0xffff0000, v126
	v_lshlrev_b32_e32 v122, 16, v123
	v_and_b32_e32 v123, 0xffff0000, v123
	v_lshlrev_b32_e32 v126, 16, v127
	v_and_b32_e32 v127, 0xffff0000, v127
	v_pk_fma_f32 v[112:113], v[112:113], v[158:159], v[154:155]
	v_pk_fma_f32 v[114:115], v[114:115], v[124:125], v[120:121]
	v_pk_fma_f32 v[116:117], v[116:117], v[162:163], v[160:161]
	v_pk_fma_f32 v[118:119], v[118:119], v[126:127], v[122:123]
	global_store_dwordx4 v[144:145], v[112:115], off offset:128
	global_store_dwordx4 v[144:145], v[116:119], off offset:144
	global_load_dwordx4 v[114:117], v[156:157], off
	s_nop 0
	global_load_dwordx4 v[118:121], v[156:157], off offset:16
	v_lshlrev_b64 v[112:113], 10, v[152:153]
	global_load_dwordx4 v[122:125], v[156:157], off offset:48
	global_load_dwordx4 v[152:155], v[156:157], off offset:32
	v_lshl_add_u64 v[112:113], v[112:113], 0, v[140:141]
	v_lshlrev_b64 v[126:127], 1, v[112:113]
	v_lshl_add_u64 v[144:145], s[16:17], 0, v[126:127]
	v_lshl_add_u64 v[126:127], s[14:15], 0, v[126:127]
	global_load_dwordx4 v[156:159], v[144:145], off
	global_load_dwordx4 v[160:163], v[126:127], off
	v_lshl_add_u64 v[112:113], v[112:113], 2, s[30:31]
	s_waitcnt vmcnt(5)
	v_mov_b32_e32 v164, v115
	v_mov_b32_e32 v165, v116
	v_mov_b32_e32 v115, v117
	s_waitcnt vmcnt(4)
	v_mov_b32_e32 v116, v119
	v_mov_b32_e32 v117, v120
	v_mov_b32_e32 v119, v121
	v_pk_add_f32 v[114:115], v[164:165], v[114:115]
	v_pk_add_f32 v[116:117], v[116:117], v[118:119]
	v_pk_add_f32 v[114:115], v[114:115], v[114:115] op_sel:[0,1] op_sel_hi:[1,0]
	v_pk_add_f32 v[116:117], v[116:117], v[116:117] op_sel:[0,1] op_sel_hi:[1,0]
	s_waitcnt vmcnt(2)
	v_add_f32_e32 v120, v152, v153
	v_add_f32_e32 v152, v154, v155
	v_mov_b32_e32 v121, v124
	v_mov_b32_e32 v153, v125
	v_mov_b32_e32 v115, v122
	v_mov_b32_e32 v117, v123
	v_pk_add_f32 v[118:119], v[120:121], v[152:153]
	v_pk_add_f32 v[114:115], v[114:115], v[116:117]
	s_waitcnt vmcnt(1)
	v_lshlrev_b32_e32 v124, 16, v156
	v_pk_add_f32 v[114:115], v[114:115], v[118:119]
	v_and_b32_e32 v125, 0xffff0000, v156
	v_add_f32_e32 v114, v114, v115
	v_fmamk_f32 v114, v114, 0x3a800000, v150
	v_mul_f32_e32 v115, 0x4b800000, v114
	v_cmp_gt_f32_e32 vcc, s48, v114
	s_waitcnt vmcnt(0)
	v_lshlrev_b32_e32 v154, 16, v160
	v_and_b32_e32 v155, 0xffff0000, v160
	v_cndmask_b32_e32 v114, v114, v115, vcc
	v_rsq_f32_e32 v116, v114
	v_lshlrev_b32_e32 v156, 16, v157
	v_and_b32_e32 v157, 0xffff0000, v157
	v_lshlrev_b32_e32 v160, 16, v161
	v_mul_f32_e32 v117, 0x45800000, v116
	v_cndmask_b32_e32 v116, v116, v117, vcc
	v_pk_mul_f32 v[110:111], v[110:111], v[116:117] op_sel_hi:[1,0]
	v_pk_mul_f32 v[108:109], v[108:109], v[116:117] op_sel_hi:[1,0]
	v_pk_mul_f32 v[106:107], v[106:107], v[116:117] op_sel_hi:[1,0]
	v_pk_mul_f32 v[104:105], v[104:105], v[116:117] op_sel_hi:[1,0]
	v_mul_f32_e32 v108, 0xbfb8aa3b, v108
	v_mul_f32_e32 v109, 0xbfb8aa3b, v109
	v_mul_f32_e32 v110, 0xbfb8aa3b, v110
	v_mul_f32_e32 v111, 0xbfb8aa3b, v111
	v_mul_f32_e32 v104, 0xbfb8aa3b, v104
	v_mul_f32_e32 v105, 0xbfb8aa3b, v105
	v_mul_f32_e32 v106, 0xbfb8aa3b, v106
	v_mul_f32_e32 v107, 0xbfb8aa3b, v107
	v_exp_f32_e32 v108, v108
	v_exp_f32_e32 v109, v109
	v_exp_f32_e32 v110, v110
	v_exp_f32_e32 v111, v111
	v_exp_f32_e32 v104, v104
	v_exp_f32_e32 v105, v105
	v_exp_f32_e32 v106, v106
	v_exp_f32_e32 v107, v107
	v_add_f32_e32 v108, 1.0, v108
	v_add_f32_e32 v109, 1.0, v109
	v_add_f32_e32 v110, 1.0, v110
	v_add_f32_e32 v111, 1.0, v111
	v_add_f32_e32 v117, 1.0, v104
	v_add_f32_e32 v118, 1.0, v105
	v_add_f32_e32 v119, 1.0, v106
	v_add_f32_e32 v120, 1.0, v107
	v_rcp_f32_e32 v104, v108
	v_rcp_f32_e32 v105, v109
	v_rcp_f32_e32 v106, v110
	v_rcp_f32_e32 v107, v111
	v_rcp_f32_e32 v108, v117
	v_rcp_f32_e32 v109, v118
	v_rcp_f32_e32 v110, v119
	v_rcp_f32_e32 v111, v120
	v_and_b32_e32 v161, 0xffff0000, v161
	v_lshlrev_b32_e32 v166, 16, v158
	v_and_b32_e32 v167, 0xffff0000, v158
	v_lshlrev_b32_e32 v168, 16, v162
	v_and_b32_e32 v169, 0xffff0000, v162
	v_lshlrev_b32_e32 v158, 16, v159
	v_and_b32_e32 v159, 0xffff0000, v159
	v_lshlrev_b32_e32 v114, 16, v163
	v_and_b32_e32 v115, 0xffff0000, v163
	v_pk_fma_f32 v[104:105], v[104:105], v[154:155], v[124:125]
	v_pk_fma_f32 v[106:107], v[106:107], v[160:161], v[156:157]
	v_pk_fma_f32 v[108:109], v[108:109], v[168:169], v[166:167]
	v_pk_fma_f32 v[110:111], v[110:111], v[114:115], v[158:159]
	global_store_dwordx4 v[112:113], v[104:107], off
	global_store_dwordx4 v[112:113], v[108:111], off offset:16
	global_load_dwordx4 v[104:107], v[144:145], off offset:64
	s_nop 0
	global_load_dwordx4 v[108:111], v[126:127], off offset:64
	v_pk_mul_f32 v[102:103], v[102:103], v[116:117] op_sel_hi:[1,0]
	v_pk_mul_f32 v[100:101], v[100:101], v[116:117] op_sel_hi:[1,0]
	v_pk_mul_f32 v[98:99], v[98:99], v[116:117] op_sel_hi:[1,0]
	v_pk_mul_f32 v[96:97], v[96:97], v[116:117] op_sel_hi:[1,0]
	v_mul_f32_e32 v100, 0xbfb8aa3b, v100
	v_mul_f32_e32 v101, 0xbfb8aa3b, v101
	v_mul_f32_e32 v102, 0xbfb8aa3b, v102
	v_mul_f32_e32 v103, 0xbfb8aa3b, v103
	v_mul_f32_e32 v96, 0xbfb8aa3b, v96
	v_mul_f32_e32 v97, 0xbfb8aa3b, v97
	v_mul_f32_e32 v98, 0xbfb8aa3b, v98
	v_mul_f32_e32 v99, 0xbfb8aa3b, v99
	v_exp_f32_e32 v100, v100
	v_exp_f32_e32 v101, v101
	v_exp_f32_e32 v102, v102
	v_exp_f32_e32 v103, v103
	v_exp_f32_e32 v96, v96
	v_exp_f32_e32 v97, v97
	v_exp_f32_e32 v98, v98
	v_exp_f32_e32 v99, v99
	v_add_f32_e32 v100, 1.0, v100
	v_add_f32_e32 v101, 1.0, v101
	v_add_f32_e32 v102, 1.0, v102
	v_add_f32_e32 v103, 1.0, v103
	v_add_f32_e32 v116, 1.0, v96
	v_add_f32_e32 v117, 1.0, v97
	v_add_f32_e32 v120, 1.0, v98
	v_add_f32_e32 v121, 1.0, v99
	v_rcp_f32_e32 v96, v100
	v_rcp_f32_e32 v97, v101
	v_rcp_f32_e32 v98, v102
	v_rcp_f32_e32 v99, v103
	v_rcp_f32_e32 v100, v116
	v_rcp_f32_e32 v101, v117
	v_rcp_f32_e32 v102, v120
	v_rcp_f32_e32 v103, v121
	v_or_b32_e32 v114, 32, v142
	v_ashrrev_i32_e32 v115, 31, v114
	v_lshlrev_b64 v[118:119], 6, v[114:115]
	v_lshl_add_u64 v[118:119], s[6:7], 0, v[118:119]
	s_waitcnt vmcnt(1)
	v_lshlrev_b32_e32 v116, 16, v104
	v_and_b32_e32 v117, 0xffff0000, v104
	s_waitcnt vmcnt(0)
	v_lshlrev_b32_e32 v120, 16, v108
	v_and_b32_e32 v121, 0xffff0000, v108
	v_lshlrev_b32_e32 v104, 16, v105
	v_and_b32_e32 v105, 0xffff0000, v105
	v_lshlrev_b32_e32 v108, 16, v109
	v_and_b32_e32 v109, 0xffff0000, v109
	v_lshlrev_b32_e32 v122, 16, v106
	v_and_b32_e32 v123, 0xffff0000, v106
	v_lshlrev_b32_e32 v124, 16, v110
	v_and_b32_e32 v125, 0xffff0000, v110
	v_lshlrev_b32_e32 v106, 16, v107
	v_and_b32_e32 v107, 0xffff0000, v107
	v_lshlrev_b32_e32 v110, 16, v111
	v_and_b32_e32 v111, 0xffff0000, v111
	v_pk_fma_f32 v[96:97], v[96:97], v[120:121], v[116:117]
	v_pk_fma_f32 v[98:99], v[98:99], v[108:109], v[104:105]
	v_pk_fma_f32 v[100:101], v[100:101], v[124:125], v[122:123]
	v_pk_fma_f32 v[102:103], v[102:103], v[110:111], v[106:107]
	global_store_dwordx4 v[112:113], v[96:99], off offset:128
	global_store_dwordx4 v[112:113], v[100:103], off offset:144
	global_load_dwordx4 v[98:101], v[118:119], off
	s_nop 0
	global_load_dwordx4 v[102:105], v[118:119], off offset:16
	global_load_dwordx4 v[106:109], v[118:119], off offset:48
	global_load_dwordx4 v[110:113], v[118:119], off offset:32
	v_lshlrev_b64 v[96:97], 10, v[114:115]
	v_lshl_add_u64 v[96:97], v[96:97], 0, v[140:141]
	v_lshlrev_b64 v[118:119], 1, v[96:97]
	v_lshl_add_u64 v[122:123], s[16:17], 0, v[118:119]
	v_lshl_add_u64 v[124:125], s[14:15], 0, v[118:119]
	global_load_dwordx4 v[114:117], v[122:123], off
	global_load_dwordx4 v[118:121], v[124:125], off
	v_lshl_add_u64 v[96:97], v[96:97], 2, s[30:31]
	s_waitcnt vmcnt(5)
	v_mov_b32_e32 v126, v99
	v_mov_b32_e32 v127, v100
	v_mov_b32_e32 v99, v101
	s_waitcnt vmcnt(4)
	v_mov_b32_e32 v100, v103
	v_mov_b32_e32 v101, v104
	v_mov_b32_e32 v103, v105
	v_pk_add_f32 v[98:99], v[126:127], v[98:99]
	v_pk_add_f32 v[100:101], v[100:101], v[102:103]
	v_pk_add_f32 v[98:99], v[98:99], v[98:99] op_sel:[0,1] op_sel_hi:[1,0]
	v_pk_add_f32 v[100:101], v[100:101], v[100:101] op_sel:[0,1] op_sel_hi:[1,0]
	s_waitcnt vmcnt(2)
	v_add_f32_e32 v104, v110, v111
	v_add_f32_e32 v110, v112, v113
	v_mov_b32_e32 v105, v108
	v_mov_b32_e32 v111, v109
	v_mov_b32_e32 v99, v106
	v_mov_b32_e32 v101, v107
	v_pk_add_f32 v[102:103], v[104:105], v[110:111]
	v_pk_add_f32 v[98:99], v[98:99], v[100:101]
	s_waitcnt vmcnt(1)
	v_lshlrev_b32_e32 v108, 16, v114
	v_pk_add_f32 v[98:99], v[98:99], v[102:103]
	v_and_b32_e32 v109, 0xffff0000, v114
	v_add_f32_e32 v98, v98, v99
	v_fmamk_f32 v98, v98, 0x3a800000, v150
	v_mul_f32_e32 v99, 0x4b800000, v98
	v_cmp_gt_f32_e32 vcc, s48, v98
	s_waitcnt vmcnt(0)
	v_lshlrev_b32_e32 v112, 16, v118
	v_and_b32_e32 v113, 0xffff0000, v118
	v_cndmask_b32_e32 v98, v98, v99, vcc
	v_rsq_f32_e32 v100, v98
	v_lshlrev_b32_e32 v114, 16, v115
	v_and_b32_e32 v115, 0xffff0000, v115
	v_lshlrev_b32_e32 v118, 16, v119
	v_mul_f32_e32 v101, 0x45800000, v100
	v_cndmask_b32_e32 v100, v100, v101, vcc
	v_pk_mul_f32 v[94:95], v[94:95], v[100:101] op_sel_hi:[1,0]
	v_pk_mul_f32 v[92:93], v[92:93], v[100:101] op_sel_hi:[1,0]
	v_pk_mul_f32 v[90:91], v[90:91], v[100:101] op_sel_hi:[1,0]
	v_pk_mul_f32 v[88:89], v[88:89], v[100:101] op_sel_hi:[1,0]
	v_mul_f32_e32 v92, 0xbfb8aa3b, v92
	v_mul_f32_e32 v93, 0xbfb8aa3b, v93
	v_mul_f32_e32 v94, 0xbfb8aa3b, v94
	v_mul_f32_e32 v95, 0xbfb8aa3b, v95
	v_mul_f32_e32 v88, 0xbfb8aa3b, v88
	v_mul_f32_e32 v89, 0xbfb8aa3b, v89
	v_mul_f32_e32 v90, 0xbfb8aa3b, v90
	v_mul_f32_e32 v91, 0xbfb8aa3b, v91
	v_exp_f32_e32 v92, v92
	v_exp_f32_e32 v93, v93
	v_exp_f32_e32 v94, v94
	v_exp_f32_e32 v95, v95
	v_exp_f32_e32 v88, v88
	v_exp_f32_e32 v89, v89
	v_exp_f32_e32 v90, v90
	v_exp_f32_e32 v91, v91
	v_add_f32_e32 v92, 1.0, v92
	v_add_f32_e32 v93, 1.0, v93
	v_add_f32_e32 v94, 1.0, v94
	v_add_f32_e32 v95, 1.0, v95
	v_add_f32_e32 v101, 1.0, v88
	v_add_f32_e32 v102, 1.0, v89
	v_add_f32_e32 v103, 1.0, v90
	v_add_f32_e32 v104, 1.0, v91
	v_rcp_f32_e32 v88, v92
	v_rcp_f32_e32 v89, v93
	v_rcp_f32_e32 v90, v94
	v_rcp_f32_e32 v91, v95
	v_rcp_f32_e32 v92, v101
	v_rcp_f32_e32 v93, v102
	v_rcp_f32_e32 v94, v103
	v_rcp_f32_e32 v95, v104
	v_and_b32_e32 v119, 0xffff0000, v119
	v_lshlrev_b32_e32 v144, 16, v116
	v_and_b32_e32 v145, 0xffff0000, v116
	v_lshlrev_b32_e32 v152, 16, v120
	v_and_b32_e32 v153, 0xffff0000, v120
	v_lshlrev_b32_e32 v116, 16, v117
	v_and_b32_e32 v117, 0xffff0000, v117
	v_lshlrev_b32_e32 v98, 16, v121
	v_and_b32_e32 v99, 0xffff0000, v121
	v_pk_fma_f32 v[88:89], v[88:89], v[112:113], v[108:109]
	v_pk_fma_f32 v[90:91], v[90:91], v[118:119], v[114:115]
	v_pk_fma_f32 v[92:93], v[92:93], v[152:153], v[144:145]
	v_pk_fma_f32 v[94:95], v[94:95], v[98:99], v[116:117]
	global_store_dwordx4 v[96:97], v[88:91], off
	global_store_dwordx4 v[96:97], v[92:95], off offset:16
	global_load_dwordx4 v[88:91], v[122:123], off offset:64
	s_nop 0
	global_load_dwordx4 v[92:95], v[124:125], off offset:64
	v_pk_mul_f32 v[86:87], v[86:87], v[100:101] op_sel_hi:[1,0]
	v_pk_mul_f32 v[84:85], v[84:85], v[100:101] op_sel_hi:[1,0]
	v_pk_mul_f32 v[82:83], v[82:83], v[100:101] op_sel_hi:[1,0]
	v_pk_mul_f32 v[80:81], v[80:81], v[100:101] op_sel_hi:[1,0]
	v_mul_f32_e32 v84, 0xbfb8aa3b, v84
	v_mul_f32_e32 v85, 0xbfb8aa3b, v85
	v_mul_f32_e32 v86, 0xbfb8aa3b, v86
	v_mul_f32_e32 v87, 0xbfb8aa3b, v87
	v_mul_f32_e32 v80, 0xbfb8aa3b, v80
	v_mul_f32_e32 v81, 0xbfb8aa3b, v81
	v_mul_f32_e32 v82, 0xbfb8aa3b, v82
	v_mul_f32_e32 v83, 0xbfb8aa3b, v83
	v_exp_f32_e32 v84, v84
	v_exp_f32_e32 v85, v85
	v_exp_f32_e32 v86, v86
	v_exp_f32_e32 v87, v87
	v_exp_f32_e32 v80, v80
	v_exp_f32_e32 v81, v81
	v_exp_f32_e32 v82, v82
	v_exp_f32_e32 v83, v83
	v_add_f32_e32 v84, 1.0, v84
	v_add_f32_e32 v85, 1.0, v85
	v_add_f32_e32 v86, 1.0, v86
	v_add_f32_e32 v87, 1.0, v87
	v_add_f32_e32 v100, 1.0, v80
	v_add_f32_e32 v101, 1.0, v81
	v_add_f32_e32 v104, 1.0, v82
	v_add_f32_e32 v105, 1.0, v83
	v_rcp_f32_e32 v80, v84
	v_rcp_f32_e32 v81, v85
	v_rcp_f32_e32 v82, v86
	v_rcp_f32_e32 v83, v87
	v_rcp_f32_e32 v84, v100
	v_rcp_f32_e32 v85, v101
	v_rcp_f32_e32 v86, v104
	v_rcp_f32_e32 v87, v105
	v_or_b32_e32 v98, 48, v142
	v_ashrrev_i32_e32 v99, 31, v98
	v_lshlrev_b64 v[102:103], 6, v[98:99]
	v_lshl_add_u64 v[102:103], s[6:7], 0, v[102:103]
	s_waitcnt vmcnt(1)
	v_lshlrev_b32_e32 v100, 16, v88
	v_and_b32_e32 v101, 0xffff0000, v88
	s_waitcnt vmcnt(0)
	v_lshlrev_b32_e32 v104, 16, v92
	v_and_b32_e32 v105, 0xffff0000, v92
	v_lshlrev_b32_e32 v88, 16, v89
	v_and_b32_e32 v89, 0xffff0000, v89
	v_lshlrev_b32_e32 v92, 16, v93
	v_and_b32_e32 v93, 0xffff0000, v93
	v_lshlrev_b32_e32 v106, 16, v90
	v_and_b32_e32 v107, 0xffff0000, v90
	v_lshlrev_b32_e32 v108, 16, v94
	v_and_b32_e32 v109, 0xffff0000, v94
	v_lshlrev_b32_e32 v90, 16, v91
	v_and_b32_e32 v91, 0xffff0000, v91
	v_lshlrev_b32_e32 v94, 16, v95
	v_and_b32_e32 v95, 0xffff0000, v95
	v_pk_fma_f32 v[80:81], v[80:81], v[104:105], v[100:101]
	v_pk_fma_f32 v[82:83], v[82:83], v[92:93], v[88:89]
	v_pk_fma_f32 v[84:85], v[84:85], v[108:109], v[106:107]
	v_pk_fma_f32 v[86:87], v[86:87], v[94:95], v[90:91]
	global_store_dwordx4 v[96:97], v[80:83], off offset:128
	global_store_dwordx4 v[96:97], v[84:87], off offset:144
	global_load_dwordx4 v[82:85], v[102:103], off
	s_nop 0
	global_load_dwordx4 v[86:89], v[102:103], off offset:16
	global_load_dwordx4 v[90:93], v[102:103], off offset:48
	global_load_dwordx4 v[94:97], v[102:103], off offset:32
	v_lshlrev_b64 v[80:81], 10, v[98:99]
	v_lshl_add_u64 v[80:81], v[80:81], 0, v[140:141]
	v_lshlrev_b64 v[102:103], 1, v[80:81]
	v_lshl_add_u64 v[106:107], s[16:17], 0, v[102:103]
	v_lshl_add_u64 v[108:109], s[14:15], 0, v[102:103]
	global_load_dwordx4 v[98:101], v[106:107], off
	global_load_dwordx4 v[102:105], v[108:109], off
	v_lshl_add_u64 v[80:81], v[80:81], 2, s[30:31]
	s_waitcnt vmcnt(5)
	v_mov_b32_e32 v110, v83
	v_mov_b32_e32 v111, v84
	v_mov_b32_e32 v83, v85
	s_waitcnt vmcnt(4)
	v_mov_b32_e32 v84, v87
	v_mov_b32_e32 v85, v88
	v_mov_b32_e32 v87, v89
	v_pk_add_f32 v[82:83], v[110:111], v[82:83]
	v_pk_add_f32 v[84:85], v[84:85], v[86:87]
	v_pk_add_f32 v[82:83], v[82:83], v[82:83] op_sel:[0,1] op_sel_hi:[1,0]
	v_pk_add_f32 v[84:85], v[84:85], v[84:85] op_sel:[0,1] op_sel_hi:[1,0]
	s_waitcnt vmcnt(2)
	v_add_f32_e32 v88, v94, v95
	v_add_f32_e32 v94, v96, v97
	v_mov_b32_e32 v89, v92
	v_mov_b32_e32 v95, v93
	v_mov_b32_e32 v83, v90
	v_mov_b32_e32 v85, v91
	v_pk_add_f32 v[86:87], v[88:89], v[94:95]
	v_pk_add_f32 v[82:83], v[82:83], v[84:85]
	s_waitcnt vmcnt(1)
	v_lshlrev_b32_e32 v92, 16, v98
	v_pk_add_f32 v[82:83], v[82:83], v[86:87]
	v_and_b32_e32 v93, 0xffff0000, v98
	v_add_f32_e32 v82, v82, v83
	v_fmamk_f32 v82, v82, 0x3a800000, v150
	v_mul_f32_e32 v83, 0x4b800000, v82
	v_cmp_gt_f32_e32 vcc, s48, v82
	s_waitcnt vmcnt(0)
	v_lshlrev_b32_e32 v96, 16, v102
	v_and_b32_e32 v97, 0xffff0000, v102
	v_cndmask_b32_e32 v82, v82, v83, vcc
	v_rsq_f32_e32 v84, v82
	v_lshlrev_b32_e32 v98, 16, v99
	v_and_b32_e32 v99, 0xffff0000, v99
	v_lshlrev_b32_e32 v102, 16, v103
	v_mul_f32_e32 v85, 0x45800000, v84
	v_cndmask_b32_e32 v84, v84, v85, vcc
	v_pk_mul_f32 v[78:79], v[78:79], v[84:85] op_sel_hi:[1,0]
	v_pk_mul_f32 v[76:77], v[76:77], v[84:85] op_sel_hi:[1,0]
	v_pk_mul_f32 v[74:75], v[74:75], v[84:85] op_sel_hi:[1,0]
	v_pk_mul_f32 v[72:73], v[72:73], v[84:85] op_sel_hi:[1,0]
	v_mul_f32_e32 v76, 0xbfb8aa3b, v76
	v_mul_f32_e32 v77, 0xbfb8aa3b, v77
	v_mul_f32_e32 v78, 0xbfb8aa3b, v78
	v_mul_f32_e32 v79, 0xbfb8aa3b, v79
	v_mul_f32_e32 v72, 0xbfb8aa3b, v72
	v_mul_f32_e32 v73, 0xbfb8aa3b, v73
	v_mul_f32_e32 v74, 0xbfb8aa3b, v74
	v_mul_f32_e32 v75, 0xbfb8aa3b, v75
	v_exp_f32_e32 v76, v76
	v_exp_f32_e32 v77, v77
	v_exp_f32_e32 v78, v78
	v_exp_f32_e32 v79, v79
	v_exp_f32_e32 v72, v72
	v_exp_f32_e32 v73, v73
	v_exp_f32_e32 v74, v74
	v_exp_f32_e32 v75, v75
	v_add_f32_e32 v76, 1.0, v76
	v_add_f32_e32 v77, 1.0, v77
	v_add_f32_e32 v78, 1.0, v78
	v_add_f32_e32 v79, 1.0, v79
	v_add_f32_e32 v85, 1.0, v72
	v_add_f32_e32 v86, 1.0, v73
	v_add_f32_e32 v87, 1.0, v74
	v_add_f32_e32 v88, 1.0, v75
	v_rcp_f32_e32 v72, v76
	v_rcp_f32_e32 v73, v77
	v_rcp_f32_e32 v74, v78
	v_rcp_f32_e32 v75, v79
	v_rcp_f32_e32 v76, v85
	v_rcp_f32_e32 v77, v86
	v_rcp_f32_e32 v78, v87
	v_rcp_f32_e32 v79, v88
	v_and_b32_e32 v103, 0xffff0000, v103
	v_lshlrev_b32_e32 v112, 16, v100
	v_and_b32_e32 v113, 0xffff0000, v100
	v_lshlrev_b32_e32 v114, 16, v104
	v_and_b32_e32 v115, 0xffff0000, v104
	v_lshlrev_b32_e32 v100, 16, v101
	v_and_b32_e32 v101, 0xffff0000, v101
	v_lshlrev_b32_e32 v82, 16, v105
	v_and_b32_e32 v83, 0xffff0000, v105
	v_pk_fma_f32 v[72:73], v[72:73], v[96:97], v[92:93]
	v_pk_fma_f32 v[74:75], v[74:75], v[102:103], v[98:99]
	v_pk_fma_f32 v[76:77], v[76:77], v[114:115], v[112:113]
	v_pk_fma_f32 v[78:79], v[78:79], v[82:83], v[100:101]
	global_store_dwordx4 v[80:81], v[72:75], off
	global_store_dwordx4 v[80:81], v[76:79], off offset:16
	global_load_dwordx4 v[72:75], v[106:107], off offset:64
	s_nop 0
	global_load_dwordx4 v[76:79], v[108:109], off offset:64
	v_pk_mul_f32 v[70:71], v[70:71], v[84:85] op_sel_hi:[1,0]
	v_pk_mul_f32 v[68:69], v[68:69], v[84:85] op_sel_hi:[1,0]
	v_pk_mul_f32 v[66:67], v[66:67], v[84:85] op_sel_hi:[1,0]
	v_pk_mul_f32 v[64:65], v[64:65], v[84:85] op_sel_hi:[1,0]
	v_mul_f32_e32 v68, 0xbfb8aa3b, v68
	v_mul_f32_e32 v69, 0xbfb8aa3b, v69
	v_mul_f32_e32 v70, 0xbfb8aa3b, v70
	v_mul_f32_e32 v71, 0xbfb8aa3b, v71
	v_mul_f32_e32 v64, 0xbfb8aa3b, v64
	v_mul_f32_e32 v65, 0xbfb8aa3b, v65
	v_mul_f32_e32 v66, 0xbfb8aa3b, v66
	v_mul_f32_e32 v67, 0xbfb8aa3b, v67
	v_exp_f32_e32 v68, v68
	v_exp_f32_e32 v69, v69
	v_exp_f32_e32 v70, v70
	v_exp_f32_e32 v71, v71
	v_exp_f32_e32 v64, v64
	v_exp_f32_e32 v65, v65
	v_exp_f32_e32 v66, v66
	v_exp_f32_e32 v67, v67
	v_add_f32_e32 v68, 1.0, v68
	v_add_f32_e32 v69, 1.0, v69
	v_add_f32_e32 v70, 1.0, v70
	v_add_f32_e32 v71, 1.0, v71
	v_add_f32_e32 v84, 1.0, v64
	v_add_f32_e32 v85, 1.0, v65
	v_add_f32_e32 v88, 1.0, v66
	v_add_f32_e32 v89, 1.0, v67
	v_rcp_f32_e32 v64, v68
	v_rcp_f32_e32 v65, v69
	v_rcp_f32_e32 v66, v70
	v_rcp_f32_e32 v67, v71
	v_rcp_f32_e32 v68, v84
	v_rcp_f32_e32 v69, v85
	v_rcp_f32_e32 v70, v88
	v_rcp_f32_e32 v71, v89
	v_add_u32_e32 v82, 0x80, v142
	v_ashrrev_i32_e32 v83, 31, v82
	v_lshlrev_b64 v[86:87], 6, v[82:83]
	v_lshl_add_u64 v[86:87], s[6:7], 0, v[86:87]
	s_waitcnt vmcnt(1)
	v_lshlrev_b32_e32 v84, 16, v72
	v_and_b32_e32 v85, 0xffff0000, v72
	s_waitcnt vmcnt(0)
	v_lshlrev_b32_e32 v88, 16, v76
	v_and_b32_e32 v89, 0xffff0000, v76
	v_lshlrev_b32_e32 v72, 16, v73
	v_and_b32_e32 v73, 0xffff0000, v73
	v_lshlrev_b32_e32 v76, 16, v77
	v_and_b32_e32 v77, 0xffff0000, v77
	v_lshlrev_b32_e32 v90, 16, v74
	v_and_b32_e32 v91, 0xffff0000, v74
	v_lshlrev_b32_e32 v92, 16, v78
	v_and_b32_e32 v93, 0xffff0000, v78
	v_lshlrev_b32_e32 v74, 16, v75
	v_and_b32_e32 v75, 0xffff0000, v75
	v_lshlrev_b32_e32 v78, 16, v79
	v_and_b32_e32 v79, 0xffff0000, v79
	v_pk_fma_f32 v[64:65], v[64:65], v[88:89], v[84:85]
	v_pk_fma_f32 v[66:67], v[66:67], v[76:77], v[72:73]
	v_pk_fma_f32 v[68:69], v[68:69], v[92:93], v[90:91]
	v_pk_fma_f32 v[70:71], v[70:71], v[78:79], v[74:75]
	global_store_dwordx4 v[80:81], v[64:67], off offset:128
	global_store_dwordx4 v[80:81], v[68:71], off offset:144
	global_load_dwordx4 v[66:69], v[86:87], off
	s_nop 0
	global_load_dwordx4 v[70:73], v[86:87], off offset:16
	global_load_dwordx4 v[74:77], v[86:87], off offset:48
	global_load_dwordx4 v[78:81], v[86:87], off offset:32
	v_lshlrev_b64 v[64:65], 10, v[82:83]
	v_lshl_add_u64 v[64:65], v[64:65], 0, v[140:141]
	v_lshlrev_b64 v[86:87], 1, v[64:65]
	v_lshl_add_u64 v[90:91], s[16:17], 0, v[86:87]
	v_lshl_add_u64 v[92:93], s[14:15], 0, v[86:87]
	global_load_dwordx4 v[82:85], v[90:91], off
	global_load_dwordx4 v[86:89], v[92:93], off
	v_lshl_add_u64 v[64:65], v[64:65], 2, s[30:31]
	s_waitcnt vmcnt(5)
	v_mov_b32_e32 v94, v67
	v_mov_b32_e32 v95, v68
	v_mov_b32_e32 v67, v69
	s_waitcnt vmcnt(4)
	v_mov_b32_e32 v68, v71
	v_mov_b32_e32 v69, v72
	v_mov_b32_e32 v71, v73
	v_pk_add_f32 v[66:67], v[94:95], v[66:67]
	v_pk_add_f32 v[68:69], v[68:69], v[70:71]
	v_pk_add_f32 v[66:67], v[66:67], v[66:67] op_sel:[0,1] op_sel_hi:[1,0]
	v_pk_add_f32 v[68:69], v[68:69], v[68:69] op_sel:[0,1] op_sel_hi:[1,0]
	s_waitcnt vmcnt(2)
	v_add_f32_e32 v72, v78, v79
	v_add_f32_e32 v78, v80, v81
	v_mov_b32_e32 v73, v76
	v_mov_b32_e32 v79, v77
	v_mov_b32_e32 v67, v74
	v_mov_b32_e32 v69, v75
	v_pk_add_f32 v[70:71], v[72:73], v[78:79]
	v_pk_add_f32 v[66:67], v[66:67], v[68:69]
	s_waitcnt vmcnt(1)
	v_lshlrev_b32_e32 v76, 16, v82
	v_pk_add_f32 v[66:67], v[66:67], v[70:71]
	v_and_b32_e32 v77, 0xffff0000, v82
	v_add_f32_e32 v66, v66, v67
	v_fmamk_f32 v66, v66, 0x3a800000, v150
	v_mul_f32_e32 v67, 0x4b800000, v66
	v_cmp_gt_f32_e32 vcc, s48, v66
	s_waitcnt vmcnt(0)
	v_lshlrev_b32_e32 v80, 16, v86
	v_and_b32_e32 v81, 0xffff0000, v86
	v_cndmask_b32_e32 v66, v66, v67, vcc
	v_rsq_f32_e32 v68, v66
	v_lshlrev_b32_e32 v82, 16, v83
	v_and_b32_e32 v83, 0xffff0000, v83
	v_lshlrev_b32_e32 v86, 16, v87
	v_mul_f32_e32 v69, 0x45800000, v68
	v_cndmask_b32_e32 v68, v68, v69, vcc
	v_pk_mul_f32 v[62:63], v[62:63], v[68:69] op_sel_hi:[1,0]
	v_pk_mul_f32 v[60:61], v[60:61], v[68:69] op_sel_hi:[1,0]
	v_pk_mul_f32 v[58:59], v[58:59], v[68:69] op_sel_hi:[1,0]
	v_pk_mul_f32 v[56:57], v[56:57], v[68:69] op_sel_hi:[1,0]
	v_mul_f32_e32 v60, 0xbfb8aa3b, v60
	v_mul_f32_e32 v61, 0xbfb8aa3b, v61
	v_mul_f32_e32 v62, 0xbfb8aa3b, v62
	v_mul_f32_e32 v63, 0xbfb8aa3b, v63
	v_mul_f32_e32 v56, 0xbfb8aa3b, v56
	v_mul_f32_e32 v57, 0xbfb8aa3b, v57
	v_mul_f32_e32 v58, 0xbfb8aa3b, v58
	v_mul_f32_e32 v59, 0xbfb8aa3b, v59
	v_exp_f32_e32 v60, v60
	v_exp_f32_e32 v61, v61
	v_exp_f32_e32 v62, v62
	v_exp_f32_e32 v63, v63
	v_exp_f32_e32 v56, v56
	v_exp_f32_e32 v57, v57
	v_exp_f32_e32 v58, v58
	v_exp_f32_e32 v59, v59
	v_add_f32_e32 v60, 1.0, v60
	v_add_f32_e32 v61, 1.0, v61
	v_add_f32_e32 v62, 1.0, v62
	v_add_f32_e32 v63, 1.0, v63
	v_add_f32_e32 v69, 1.0, v56
	v_add_f32_e32 v70, 1.0, v57
	v_add_f32_e32 v71, 1.0, v58
	v_add_f32_e32 v72, 1.0, v59
	v_rcp_f32_e32 v56, v60
	v_rcp_f32_e32 v57, v61
	v_rcp_f32_e32 v58, v62
	v_rcp_f32_e32 v59, v63
	v_rcp_f32_e32 v60, v69
	v_rcp_f32_e32 v61, v70
	v_rcp_f32_e32 v62, v71
	v_rcp_f32_e32 v63, v72
	v_and_b32_e32 v87, 0xffff0000, v87
	v_lshlrev_b32_e32 v96, 16, v84
	v_and_b32_e32 v97, 0xffff0000, v84
	v_lshlrev_b32_e32 v98, 16, v88
	v_and_b32_e32 v99, 0xffff0000, v88
	v_lshlrev_b32_e32 v84, 16, v85
	v_and_b32_e32 v85, 0xffff0000, v85
	v_lshlrev_b32_e32 v66, 16, v89
	v_and_b32_e32 v67, 0xffff0000, v89
	v_pk_fma_f32 v[56:57], v[56:57], v[80:81], v[76:77]
	v_pk_fma_f32 v[58:59], v[58:59], v[86:87], v[82:83]
	v_pk_fma_f32 v[60:61], v[60:61], v[98:99], v[96:97]
	v_pk_fma_f32 v[62:63], v[62:63], v[66:67], v[84:85]
	global_store_dwordx4 v[64:65], v[56:59], off
	global_store_dwordx4 v[64:65], v[60:63], off offset:16
	global_load_dwordx4 v[56:59], v[90:91], off offset:64
	s_nop 0
	global_load_dwordx4 v[60:63], v[92:93], off offset:64
	v_pk_mul_f32 v[54:55], v[54:55], v[68:69] op_sel_hi:[1,0]
	v_pk_mul_f32 v[52:53], v[52:53], v[68:69] op_sel_hi:[1,0]
	v_pk_mul_f32 v[50:51], v[50:51], v[68:69] op_sel_hi:[1,0]
	v_pk_mul_f32 v[48:49], v[48:49], v[68:69] op_sel_hi:[1,0]
	v_mul_f32_e32 v52, 0xbfb8aa3b, v52
	v_mul_f32_e32 v53, 0xbfb8aa3b, v53
	v_mul_f32_e32 v54, 0xbfb8aa3b, v54
	v_mul_f32_e32 v55, 0xbfb8aa3b, v55
	v_mul_f32_e32 v48, 0xbfb8aa3b, v48
	v_mul_f32_e32 v49, 0xbfb8aa3b, v49
	v_mul_f32_e32 v50, 0xbfb8aa3b, v50
	v_mul_f32_e32 v51, 0xbfb8aa3b, v51
	v_exp_f32_e32 v52, v52
	v_exp_f32_e32 v53, v53
	v_exp_f32_e32 v54, v54
	v_exp_f32_e32 v55, v55
	v_exp_f32_e32 v48, v48
	v_exp_f32_e32 v49, v49
	v_exp_f32_e32 v50, v50
	v_exp_f32_e32 v51, v51
	v_add_f32_e32 v52, 1.0, v52
	v_add_f32_e32 v53, 1.0, v53
	v_add_f32_e32 v54, 1.0, v54
	v_add_f32_e32 v55, 1.0, v55
	v_add_f32_e32 v68, 1.0, v48
	v_add_f32_e32 v69, 1.0, v49
	v_add_f32_e32 v72, 1.0, v50
	v_add_f32_e32 v73, 1.0, v51
	v_rcp_f32_e32 v48, v52
	v_rcp_f32_e32 v49, v53
	v_rcp_f32_e32 v50, v54
	v_rcp_f32_e32 v51, v55
	v_rcp_f32_e32 v52, v68
	v_rcp_f32_e32 v53, v69
	v_rcp_f32_e32 v54, v72
	v_rcp_f32_e32 v55, v73
	v_add_u32_e32 v66, 0x90, v142
	v_ashrrev_i32_e32 v67, 31, v66
	v_lshlrev_b64 v[70:71], 6, v[66:67]
	v_lshl_add_u64 v[70:71], s[6:7], 0, v[70:71]
	s_waitcnt vmcnt(1)
	v_lshlrev_b32_e32 v68, 16, v56
	v_and_b32_e32 v69, 0xffff0000, v56
	s_waitcnt vmcnt(0)
	v_lshlrev_b32_e32 v72, 16, v60
	v_and_b32_e32 v73, 0xffff0000, v60
	v_lshlrev_b32_e32 v56, 16, v57
	v_and_b32_e32 v57, 0xffff0000, v57
	v_lshlrev_b32_e32 v60, 16, v61
	v_and_b32_e32 v61, 0xffff0000, v61
	v_lshlrev_b32_e32 v74, 16, v58
	v_and_b32_e32 v75, 0xffff0000, v58
	v_lshlrev_b32_e32 v76, 16, v62
	v_and_b32_e32 v77, 0xffff0000, v62
	v_lshlrev_b32_e32 v58, 16, v59
	v_and_b32_e32 v59, 0xffff0000, v59
	v_lshlrev_b32_e32 v62, 16, v63
	v_and_b32_e32 v63, 0xffff0000, v63
	v_pk_fma_f32 v[48:49], v[48:49], v[72:73], v[68:69]
	v_pk_fma_f32 v[50:51], v[50:51], v[60:61], v[56:57]
	v_pk_fma_f32 v[52:53], v[52:53], v[76:77], v[74:75]
	v_pk_fma_f32 v[54:55], v[54:55], v[62:63], v[58:59]
	global_store_dwordx4 v[64:65], v[48:51], off offset:128
	global_store_dwordx4 v[64:65], v[52:55], off offset:144
	global_load_dwordx4 v[50:53], v[70:71], off
	s_nop 0
	global_load_dwordx4 v[54:57], v[70:71], off offset:16
	global_load_dwordx4 v[58:61], v[70:71], off offset:48
	global_load_dwordx4 v[62:65], v[70:71], off offset:32
	v_lshlrev_b64 v[48:49], 10, v[66:67]
	v_lshl_add_u64 v[48:49], v[48:49], 0, v[140:141]
	v_lshlrev_b64 v[70:71], 1, v[48:49]
	v_lshl_add_u64 v[74:75], s[16:17], 0, v[70:71]
	v_lshl_add_u64 v[76:77], s[14:15], 0, v[70:71]
	global_load_dwordx4 v[66:69], v[74:75], off
	global_load_dwordx4 v[70:73], v[76:77], off
	v_lshl_add_u64 v[48:49], v[48:49], 2, s[30:31]
	s_waitcnt vmcnt(5)
	v_mov_b32_e32 v78, v51
	v_mov_b32_e32 v79, v52
	v_mov_b32_e32 v51, v53
	s_waitcnt vmcnt(4)
	v_mov_b32_e32 v52, v55
	v_mov_b32_e32 v53, v56
	v_mov_b32_e32 v55, v57
	v_pk_add_f32 v[50:51], v[78:79], v[50:51]
	v_pk_add_f32 v[52:53], v[52:53], v[54:55]
	v_pk_add_f32 v[50:51], v[50:51], v[50:51] op_sel:[0,1] op_sel_hi:[1,0]
	v_pk_add_f32 v[52:53], v[52:53], v[52:53] op_sel:[0,1] op_sel_hi:[1,0]
	s_waitcnt vmcnt(2)
	v_add_f32_e32 v56, v62, v63
	v_add_f32_e32 v62, v64, v65
	v_mov_b32_e32 v57, v60
	v_mov_b32_e32 v63, v61
	v_mov_b32_e32 v51, v58
	v_mov_b32_e32 v53, v59
	v_pk_add_f32 v[54:55], v[56:57], v[62:63]
	v_pk_add_f32 v[50:51], v[50:51], v[52:53]
	s_waitcnt vmcnt(1)
	v_lshlrev_b32_e32 v60, 16, v66
	v_pk_add_f32 v[50:51], v[50:51], v[54:55]
	v_and_b32_e32 v61, 0xffff0000, v66
	v_add_f32_e32 v50, v50, v51
	v_fmamk_f32 v50, v50, 0x3a800000, v150
	v_mul_f32_e32 v51, 0x4b800000, v50
	v_cmp_gt_f32_e32 vcc, s48, v50
	s_waitcnt vmcnt(0)
	v_lshlrev_b32_e32 v64, 16, v70
	v_and_b32_e32 v65, 0xffff0000, v70
	v_cndmask_b32_e32 v50, v50, v51, vcc
	v_rsq_f32_e32 v52, v50
	v_lshlrev_b32_e32 v66, 16, v67
	v_and_b32_e32 v67, 0xffff0000, v67
	v_lshlrev_b32_e32 v70, 16, v71
	v_mul_f32_e32 v53, 0x45800000, v52
	v_cndmask_b32_e32 v52, v52, v53, vcc
	v_pk_mul_f32 v[46:47], v[46:47], v[52:53] op_sel_hi:[1,0]
	v_pk_mul_f32 v[44:45], v[44:45], v[52:53] op_sel_hi:[1,0]
	v_pk_mul_f32 v[42:43], v[42:43], v[52:53] op_sel_hi:[1,0]
	v_pk_mul_f32 v[40:41], v[40:41], v[52:53] op_sel_hi:[1,0]
	v_mul_f32_e32 v44, 0xbfb8aa3b, v44
	v_mul_f32_e32 v45, 0xbfb8aa3b, v45
	v_mul_f32_e32 v46, 0xbfb8aa3b, v46
	v_mul_f32_e32 v47, 0xbfb8aa3b, v47
	v_mul_f32_e32 v40, 0xbfb8aa3b, v40
	v_mul_f32_e32 v41, 0xbfb8aa3b, v41
	v_mul_f32_e32 v42, 0xbfb8aa3b, v42
	v_mul_f32_e32 v43, 0xbfb8aa3b, v43
	v_exp_f32_e32 v44, v44
	v_exp_f32_e32 v45, v45
	v_exp_f32_e32 v46, v46
	v_exp_f32_e32 v47, v47
	v_exp_f32_e32 v40, v40
	v_exp_f32_e32 v41, v41
	v_exp_f32_e32 v42, v42
	v_exp_f32_e32 v43, v43
	v_add_f32_e32 v44, 1.0, v44
	v_add_f32_e32 v45, 1.0, v45
	v_add_f32_e32 v46, 1.0, v46
	v_add_f32_e32 v47, 1.0, v47
	v_add_f32_e32 v53, 1.0, v40
	v_add_f32_e32 v54, 1.0, v41
	v_add_f32_e32 v55, 1.0, v42
	v_add_f32_e32 v56, 1.0, v43
	v_rcp_f32_e32 v40, v44
	v_rcp_f32_e32 v41, v45
	v_rcp_f32_e32 v42, v46
	v_rcp_f32_e32 v43, v47
	v_rcp_f32_e32 v44, v53
	v_rcp_f32_e32 v45, v54
	v_rcp_f32_e32 v46, v55
	v_rcp_f32_e32 v47, v56
	v_and_b32_e32 v71, 0xffff0000, v71
	v_lshlrev_b32_e32 v80, 16, v68
	v_and_b32_e32 v81, 0xffff0000, v68
	v_lshlrev_b32_e32 v82, 16, v72
	v_and_b32_e32 v83, 0xffff0000, v72
	v_lshlrev_b32_e32 v68, 16, v69
	v_and_b32_e32 v69, 0xffff0000, v69
	v_lshlrev_b32_e32 v50, 16, v73
	v_and_b32_e32 v51, 0xffff0000, v73
	v_pk_fma_f32 v[40:41], v[40:41], v[64:65], v[60:61]
	v_pk_fma_f32 v[42:43], v[42:43], v[70:71], v[66:67]
	v_pk_fma_f32 v[44:45], v[44:45], v[82:83], v[80:81]
	v_pk_fma_f32 v[46:47], v[46:47], v[50:51], v[68:69]
	global_store_dwordx4 v[48:49], v[40:43], off
	global_store_dwordx4 v[48:49], v[44:47], off offset:16
	global_load_dwordx4 v[40:43], v[74:75], off offset:64
	s_nop 0
	global_load_dwordx4 v[44:47], v[76:77], off offset:64
	v_pk_mul_f32 v[38:39], v[38:39], v[52:53] op_sel_hi:[1,0]
	v_pk_mul_f32 v[36:37], v[36:37], v[52:53] op_sel_hi:[1,0]
	v_pk_mul_f32 v[34:35], v[34:35], v[52:53] op_sel_hi:[1,0]
	v_pk_mul_f32 v[32:33], v[32:33], v[52:53] op_sel_hi:[1,0]
	v_mul_f32_e32 v36, 0xbfb8aa3b, v36
	v_mul_f32_e32 v37, 0xbfb8aa3b, v37
	v_mul_f32_e32 v38, 0xbfb8aa3b, v38
	v_mul_f32_e32 v39, 0xbfb8aa3b, v39
	v_mul_f32_e32 v32, 0xbfb8aa3b, v32
	v_mul_f32_e32 v33, 0xbfb8aa3b, v33
	v_mul_f32_e32 v34, 0xbfb8aa3b, v34
	v_mul_f32_e32 v35, 0xbfb8aa3b, v35
	v_exp_f32_e32 v36, v36
	v_exp_f32_e32 v37, v37
	v_exp_f32_e32 v38, v38
	v_exp_f32_e32 v39, v39
	v_exp_f32_e32 v32, v32
	v_exp_f32_e32 v33, v33
	v_exp_f32_e32 v34, v34
	v_exp_f32_e32 v35, v35
	v_add_f32_e32 v36, 1.0, v36
	v_add_f32_e32 v37, 1.0, v37
	v_add_f32_e32 v38, 1.0, v38
	v_add_f32_e32 v39, 1.0, v39
	v_add_f32_e32 v52, 1.0, v32
	v_add_f32_e32 v53, 1.0, v33
	v_add_f32_e32 v56, 1.0, v34
	v_add_f32_e32 v57, 1.0, v35
	v_rcp_f32_e32 v32, v36
	v_rcp_f32_e32 v33, v37
	v_rcp_f32_e32 v34, v38
	v_rcp_f32_e32 v35, v39
	v_rcp_f32_e32 v36, v52
	v_rcp_f32_e32 v37, v53
	v_rcp_f32_e32 v38, v56
	v_rcp_f32_e32 v39, v57
	v_add_u32_e32 v50, 0xa0, v142
	v_ashrrev_i32_e32 v51, 31, v50
	v_lshlrev_b64 v[54:55], 6, v[50:51]
	v_lshl_add_u64 v[54:55], s[6:7], 0, v[54:55]
	s_waitcnt vmcnt(1)
	v_lshlrev_b32_e32 v52, 16, v40
	v_and_b32_e32 v53, 0xffff0000, v40
	s_waitcnt vmcnt(0)
	v_lshlrev_b32_e32 v56, 16, v44
	v_and_b32_e32 v57, 0xffff0000, v44
	v_lshlrev_b32_e32 v40, 16, v41
	v_and_b32_e32 v41, 0xffff0000, v41
	v_lshlrev_b32_e32 v44, 16, v45
	v_and_b32_e32 v45, 0xffff0000, v45
	v_lshlrev_b32_e32 v58, 16, v42
	v_and_b32_e32 v59, 0xffff0000, v42
	v_lshlrev_b32_e32 v60, 16, v46
	v_and_b32_e32 v61, 0xffff0000, v46
	v_lshlrev_b32_e32 v42, 16, v43
	v_and_b32_e32 v43, 0xffff0000, v43
	v_lshlrev_b32_e32 v46, 16, v47
	v_and_b32_e32 v47, 0xffff0000, v47
	v_pk_fma_f32 v[32:33], v[32:33], v[56:57], v[52:53]
	v_pk_fma_f32 v[34:35], v[34:35], v[44:45], v[40:41]
	v_pk_fma_f32 v[36:37], v[36:37], v[60:61], v[58:59]
	v_pk_fma_f32 v[38:39], v[38:39], v[46:47], v[42:43]
	global_store_dwordx4 v[48:49], v[32:35], off offset:128
	global_store_dwordx4 v[48:49], v[36:39], off offset:144
	global_load_dwordx4 v[34:37], v[54:55], off
	s_nop 0
	global_load_dwordx4 v[38:41], v[54:55], off offset:16
	global_load_dwordx4 v[42:45], v[54:55], off offset:48
	global_load_dwordx4 v[46:49], v[54:55], off offset:32
	v_lshlrev_b64 v[32:33], 10, v[50:51]
	v_lshl_add_u64 v[32:33], v[32:33], 0, v[140:141]
	v_lshlrev_b64 v[54:55], 1, v[32:33]
	v_lshl_add_u64 v[58:59], s[16:17], 0, v[54:55]
	v_lshl_add_u64 v[60:61], s[14:15], 0, v[54:55]
	global_load_dwordx4 v[50:53], v[58:59], off
	global_load_dwordx4 v[54:57], v[60:61], off
	v_lshl_add_u64 v[32:33], v[32:33], 2, s[30:31]
	s_waitcnt vmcnt(5)
	v_mov_b32_e32 v62, v35
	v_mov_b32_e32 v63, v36
	v_mov_b32_e32 v35, v37
	s_waitcnt vmcnt(4)
	v_mov_b32_e32 v36, v39
	v_mov_b32_e32 v37, v40
	v_mov_b32_e32 v39, v41
	v_pk_add_f32 v[34:35], v[62:63], v[34:35]
	v_pk_add_f32 v[36:37], v[36:37], v[38:39]
	v_pk_add_f32 v[34:35], v[34:35], v[34:35] op_sel:[0,1] op_sel_hi:[1,0]
	v_pk_add_f32 v[36:37], v[36:37], v[36:37] op_sel:[0,1] op_sel_hi:[1,0]
	s_waitcnt vmcnt(2)
	v_add_f32_e32 v40, v46, v47
	v_add_f32_e32 v46, v48, v49
	v_mov_b32_e32 v41, v44
	v_mov_b32_e32 v47, v45
	v_mov_b32_e32 v35, v42
	v_mov_b32_e32 v37, v43
	v_pk_add_f32 v[38:39], v[40:41], v[46:47]
	v_pk_add_f32 v[34:35], v[34:35], v[36:37]
	s_waitcnt vmcnt(1)
	v_lshlrev_b32_e32 v44, 16, v50
	v_pk_add_f32 v[34:35], v[34:35], v[38:39]
	v_and_b32_e32 v45, 0xffff0000, v50
	v_add_f32_e32 v34, v34, v35
	v_fmamk_f32 v34, v34, 0x3a800000, v150
	v_mul_f32_e32 v35, 0x4b800000, v34
	v_cmp_gt_f32_e32 vcc, s48, v34
	s_waitcnt vmcnt(0)
	v_lshlrev_b32_e32 v48, 16, v54
	v_and_b32_e32 v49, 0xffff0000, v54
	v_cndmask_b32_e32 v34, v34, v35, vcc
	v_rsq_f32_e32 v36, v34
	v_lshlrev_b32_e32 v50, 16, v51
	v_and_b32_e32 v51, 0xffff0000, v51
	v_lshlrev_b32_e32 v54, 16, v55
	v_mul_f32_e32 v37, 0x45800000, v36
	v_cndmask_b32_e32 v36, v36, v37, vcc
	v_pk_mul_f32 v[30:31], v[30:31], v[36:37] op_sel_hi:[1,0]
	v_pk_mul_f32 v[28:29], v[28:29], v[36:37] op_sel_hi:[1,0]
	v_pk_mul_f32 v[26:27], v[26:27], v[36:37] op_sel_hi:[1,0]
	v_pk_mul_f32 v[24:25], v[24:25], v[36:37] op_sel_hi:[1,0]
	v_mul_f32_e32 v28, 0xbfb8aa3b, v28
	v_mul_f32_e32 v29, 0xbfb8aa3b, v29
	v_mul_f32_e32 v30, 0xbfb8aa3b, v30
	v_mul_f32_e32 v31, 0xbfb8aa3b, v31
	v_mul_f32_e32 v24, 0xbfb8aa3b, v24
	v_mul_f32_e32 v25, 0xbfb8aa3b, v25
	v_mul_f32_e32 v26, 0xbfb8aa3b, v26
	v_mul_f32_e32 v27, 0xbfb8aa3b, v27
	v_exp_f32_e32 v28, v28
	v_exp_f32_e32 v29, v29
	v_exp_f32_e32 v30, v30
	v_exp_f32_e32 v31, v31
	v_exp_f32_e32 v24, v24
	v_exp_f32_e32 v25, v25
	v_exp_f32_e32 v26, v26
	v_exp_f32_e32 v27, v27
	v_add_f32_e32 v28, 1.0, v28
	v_add_f32_e32 v29, 1.0, v29
	v_add_f32_e32 v30, 1.0, v30
	v_add_f32_e32 v31, 1.0, v31
	v_add_f32_e32 v37, 1.0, v24
	v_add_f32_e32 v38, 1.0, v25
	v_add_f32_e32 v39, 1.0, v26
	v_add_f32_e32 v40, 1.0, v27
	v_rcp_f32_e32 v24, v28
	v_rcp_f32_e32 v25, v29
	v_rcp_f32_e32 v26, v30
	v_rcp_f32_e32 v27, v31
	v_rcp_f32_e32 v28, v37
	v_rcp_f32_e32 v29, v38
	v_rcp_f32_e32 v30, v39
	v_rcp_f32_e32 v31, v40
	v_and_b32_e32 v55, 0xffff0000, v55
	v_lshlrev_b32_e32 v64, 16, v52
	v_and_b32_e32 v65, 0xffff0000, v52
	v_lshlrev_b32_e32 v66, 16, v56
	v_and_b32_e32 v67, 0xffff0000, v56
	v_lshlrev_b32_e32 v52, 16, v53
	v_and_b32_e32 v53, 0xffff0000, v53
	v_lshlrev_b32_e32 v34, 16, v57
	v_and_b32_e32 v35, 0xffff0000, v57
	v_pk_fma_f32 v[24:25], v[24:25], v[48:49], v[44:45]
	v_pk_fma_f32 v[26:27], v[26:27], v[54:55], v[50:51]
	v_pk_fma_f32 v[28:29], v[28:29], v[66:67], v[64:65]
	v_pk_fma_f32 v[30:31], v[30:31], v[34:35], v[52:53]
	global_store_dwordx4 v[32:33], v[24:27], off
	global_store_dwordx4 v[32:33], v[28:31], off offset:16
	global_load_dwordx4 v[24:27], v[58:59], off offset:64
	s_nop 0
	global_load_dwordx4 v[28:31], v[60:61], off offset:64
	v_pk_mul_f32 v[22:23], v[22:23], v[36:37] op_sel_hi:[1,0]
	v_pk_mul_f32 v[20:21], v[20:21], v[36:37] op_sel_hi:[1,0]
	v_pk_mul_f32 v[18:19], v[18:19], v[36:37] op_sel_hi:[1,0]
	v_pk_mul_f32 v[16:17], v[16:17], v[36:37] op_sel_hi:[1,0]
	v_mul_f32_e32 v20, 0xbfb8aa3b, v20
	v_mul_f32_e32 v21, 0xbfb8aa3b, v21
	v_mul_f32_e32 v22, 0xbfb8aa3b, v22
	v_mul_f32_e32 v23, 0xbfb8aa3b, v23
	v_mul_f32_e32 v16, 0xbfb8aa3b, v16
	v_mul_f32_e32 v17, 0xbfb8aa3b, v17
	v_mul_f32_e32 v18, 0xbfb8aa3b, v18
	v_mul_f32_e32 v19, 0xbfb8aa3b, v19
	v_exp_f32_e32 v20, v20
	v_exp_f32_e32 v21, v21
	v_exp_f32_e32 v22, v22
	v_exp_f32_e32 v23, v23
	v_exp_f32_e32 v16, v16
	v_exp_f32_e32 v17, v17
	v_exp_f32_e32 v18, v18
	v_exp_f32_e32 v19, v19
	v_add_f32_e32 v20, 1.0, v20
	v_add_f32_e32 v21, 1.0, v21
	v_add_f32_e32 v22, 1.0, v22
	v_add_f32_e32 v23, 1.0, v23
	v_add_f32_e32 v36, 1.0, v16
	v_add_f32_e32 v37, 1.0, v17
	v_add_f32_e32 v40, 1.0, v18
	v_add_f32_e32 v41, 1.0, v19
	v_rcp_f32_e32 v16, v20
	v_rcp_f32_e32 v17, v21
	v_rcp_f32_e32 v18, v22
	v_rcp_f32_e32 v19, v23
	v_rcp_f32_e32 v20, v36
	v_rcp_f32_e32 v21, v37
	v_rcp_f32_e32 v22, v40
	v_rcp_f32_e32 v23, v41
	v_add_u32_e32 v34, 0xb0, v142
	v_ashrrev_i32_e32 v35, 31, v34
	v_lshlrev_b64 v[38:39], 6, v[34:35]
	v_lshl_add_u64 v[38:39], s[6:7], 0, v[38:39]
	s_waitcnt vmcnt(1)
	v_lshlrev_b32_e32 v36, 16, v24
	v_and_b32_e32 v37, 0xffff0000, v24
	s_waitcnt vmcnt(0)
	v_lshlrev_b32_e32 v40, 16, v28
	v_and_b32_e32 v41, 0xffff0000, v28
	v_lshlrev_b32_e32 v24, 16, v25
	v_and_b32_e32 v25, 0xffff0000, v25
	v_lshlrev_b32_e32 v28, 16, v29
	v_and_b32_e32 v29, 0xffff0000, v29
	v_lshlrev_b32_e32 v42, 16, v26
	v_and_b32_e32 v43, 0xffff0000, v26
	v_lshlrev_b32_e32 v44, 16, v30
	v_and_b32_e32 v45, 0xffff0000, v30
	v_lshlrev_b32_e32 v26, 16, v27
	v_and_b32_e32 v27, 0xffff0000, v27
	v_lshlrev_b32_e32 v30, 16, v31
	v_and_b32_e32 v31, 0xffff0000, v31
	v_pk_fma_f32 v[16:17], v[16:17], v[40:41], v[36:37]
	v_pk_fma_f32 v[18:19], v[18:19], v[28:29], v[24:25]
	v_pk_fma_f32 v[20:21], v[20:21], v[44:45], v[42:43]
	v_pk_fma_f32 v[22:23], v[22:23], v[30:31], v[26:27]
	global_store_dwordx4 v[32:33], v[16:19], off offset:128
	global_store_dwordx4 v[32:33], v[20:23], off offset:144
	global_load_dwordx4 v[16:19], v[38:39], off
	s_nop 0
	global_load_dwordx4 v[20:23], v[38:39], off offset:16
	global_load_dwordx4 v[24:27], v[38:39], off offset:48
	global_load_dwordx4 v[28:31], v[38:39], off offset:32
	v_lshlrev_b64 v[32:33], 10, v[34:35]
	v_lshl_add_u64 v[40:41], v[32:33], 0, v[140:141]
	v_lshlrev_b64 v[36:37], 1, v[40:41]
	v_lshl_add_u64 v[42:43], s[16:17], 0, v[36:37]
	v_lshl_add_u64 v[44:45], s[14:15], 0, v[36:37]
	global_load_dwordx4 v[32:35], v[42:43], off
	global_load_dwordx4 v[36:39], v[44:45], off
	v_lshl_add_u64 v[40:41], v[40:41], 2, s[30:31]
	s_waitcnt vmcnt(5)
	v_mov_b32_e32 v46, v17
	v_mov_b32_e32 v47, v18
	v_mov_b32_e32 v17, v19
	s_waitcnt vmcnt(4)
	v_mov_b32_e32 v18, v21
	v_mov_b32_e32 v19, v22
	v_mov_b32_e32 v21, v23
	v_pk_add_f32 v[16:17], v[46:47], v[16:17]
	v_pk_add_f32 v[18:19], v[18:19], v[20:21]
	v_pk_add_f32 v[16:17], v[16:17], v[16:17] op_sel:[0,1] op_sel_hi:[1,0]
	v_pk_add_f32 v[18:19], v[18:19], v[18:19] op_sel:[0,1] op_sel_hi:[1,0]
	s_waitcnt vmcnt(2)
	v_add_f32_e32 v22, v28, v29
	v_add_f32_e32 v28, v30, v31
	v_mov_b32_e32 v23, v26
	v_mov_b32_e32 v29, v27
	v_mov_b32_e32 v17, v24
	v_mov_b32_e32 v19, v25
	v_pk_add_f32 v[20:21], v[22:23], v[28:29]
	v_pk_add_f32 v[16:17], v[16:17], v[18:19]
	s_waitcnt vmcnt(1)
	v_lshlrev_b32_e32 v26, 16, v32
	v_pk_add_f32 v[16:17], v[16:17], v[20:21]
	v_and_b32_e32 v27, 0xffff0000, v32
	v_add_f32_e32 v16, v16, v17
	v_fmamk_f32 v16, v16, 0x3a800000, v150
	v_mul_f32_e32 v17, 0x4b800000, v16
	v_cmp_gt_f32_e32 vcc, s48, v16
	s_waitcnt vmcnt(0)
	v_lshlrev_b32_e32 v30, 16, v36
	v_and_b32_e32 v31, 0xffff0000, v36
	v_cndmask_b32_e32 v16, v16, v17, vcc
	v_rsq_f32_e32 v18, v16
	v_lshlrev_b32_e32 v32, 16, v33
	v_and_b32_e32 v33, 0xffff0000, v33
	v_lshlrev_b32_e32 v36, 16, v37
	v_mul_f32_e32 v19, 0x45800000, v18
	v_cndmask_b32_e32 v18, v18, v19, vcc
	v_pk_mul_f32 v[14:15], v[14:15], v[18:19] op_sel_hi:[1,0]
	v_pk_mul_f32 v[12:13], v[12:13], v[18:19] op_sel_hi:[1,0]
	v_pk_mul_f32 v[10:11], v[10:11], v[18:19] op_sel_hi:[1,0]
	v_pk_mul_f32 v[8:9], v[8:9], v[18:19] op_sel_hi:[1,0]
	v_mul_f32_e32 v12, 0xbfb8aa3b, v12
	v_mul_f32_e32 v13, 0xbfb8aa3b, v13
	v_mul_f32_e32 v14, 0xbfb8aa3b, v14
	v_mul_f32_e32 v15, 0xbfb8aa3b, v15
	v_mul_f32_e32 v8, 0xbfb8aa3b, v8
	v_mul_f32_e32 v9, 0xbfb8aa3b, v9
	v_mul_f32_e32 v10, 0xbfb8aa3b, v10
	v_mul_f32_e32 v11, 0xbfb8aa3b, v11
	v_exp_f32_e32 v12, v12
	v_exp_f32_e32 v13, v13
	v_exp_f32_e32 v14, v14
	v_exp_f32_e32 v15, v15
	v_exp_f32_e32 v8, v8
	v_exp_f32_e32 v9, v9
	v_exp_f32_e32 v10, v10
	v_exp_f32_e32 v11, v11
	v_add_f32_e32 v12, 1.0, v12
	v_add_f32_e32 v13, 1.0, v13
	v_add_f32_e32 v14, 1.0, v14
	v_add_f32_e32 v15, 1.0, v15
	v_add_f32_e32 v19, 1.0, v8
	v_add_f32_e32 v20, 1.0, v9
	v_add_f32_e32 v21, 1.0, v10
	v_add_f32_e32 v22, 1.0, v11
	v_rcp_f32_e32 v8, v12
	v_rcp_f32_e32 v9, v13
	v_rcp_f32_e32 v10, v14
	v_rcp_f32_e32 v11, v15
	v_rcp_f32_e32 v12, v19
	v_rcp_f32_e32 v13, v20
	v_rcp_f32_e32 v14, v21
	v_rcp_f32_e32 v15, v22
	v_and_b32_e32 v37, 0xffff0000, v37
	v_lshlrev_b32_e32 v48, 16, v34
	v_and_b32_e32 v49, 0xffff0000, v34
	v_lshlrev_b32_e32 v50, 16, v38
	v_and_b32_e32 v51, 0xffff0000, v38
	v_lshlrev_b32_e32 v34, 16, v35
	v_and_b32_e32 v35, 0xffff0000, v35
	v_lshlrev_b32_e32 v16, 16, v39
	v_and_b32_e32 v17, 0xffff0000, v39
	v_pk_fma_f32 v[8:9], v[8:9], v[30:31], v[26:27]
	v_pk_fma_f32 v[10:11], v[10:11], v[36:37], v[32:33]
	v_pk_fma_f32 v[12:13], v[12:13], v[50:51], v[48:49]
	v_pk_fma_f32 v[14:15], v[14:15], v[16:17], v[34:35]
	global_store_dwordx4 v[40:41], v[8:11], off
	global_store_dwordx4 v[40:41], v[12:15], off offset:16
	global_load_dwordx4 v[8:11], v[42:43], off offset:64
	s_nop 0
	global_load_dwordx4 v[12:15], v[44:45], off offset:64
	v_pk_mul_f32 v[6:7], v[6:7], v[18:19] op_sel_hi:[1,0]
	v_pk_mul_f32 v[4:5], v[4:5], v[18:19] op_sel_hi:[1,0]
	v_pk_mul_f32 v[2:3], v[2:3], v[18:19] op_sel_hi:[1,0]
	v_pk_mul_f32 v[0:1], v[0:1], v[18:19] op_sel_hi:[1,0]
	v_mul_f32_e32 v4, 0xbfb8aa3b, v4
	v_mul_f32_e32 v5, 0xbfb8aa3b, v5
	v_mul_f32_e32 v6, 0xbfb8aa3b, v6
	v_mul_f32_e32 v7, 0xbfb8aa3b, v7
	v_mul_f32_e32 v0, 0xbfb8aa3b, v0
	v_mul_f32_e32 v1, 0xbfb8aa3b, v1
	v_mul_f32_e32 v2, 0xbfb8aa3b, v2
	v_mul_f32_e32 v3, 0xbfb8aa3b, v3
	v_exp_f32_e32 v4, v4
	v_exp_f32_e32 v5, v5
	v_exp_f32_e32 v6, v6
	v_exp_f32_e32 v7, v7
	v_exp_f32_e32 v0, v0
	v_exp_f32_e32 v1, v1
	v_exp_f32_e32 v2, v2
	v_exp_f32_e32 v3, v3
	v_add_f32_e32 v4, 1.0, v4
	v_add_f32_e32 v5, 1.0, v5
	v_add_f32_e32 v6, 1.0, v6
	v_add_f32_e32 v7, 1.0, v7
	v_add_f32_e32 v16, 1.0, v0
	v_add_f32_e32 v17, 1.0, v1
	v_add_f32_e32 v18, 1.0, v2
	v_add_f32_e32 v19, 1.0, v3
	v_rcp_f32_e32 v0, v4
	v_rcp_f32_e32 v1, v5
	v_rcp_f32_e32 v2, v6
	v_rcp_f32_e32 v3, v7
	v_rcp_f32_e32 v4, v16
	v_rcp_f32_e32 v5, v17
	v_rcp_f32_e32 v6, v18
	v_rcp_f32_e32 v7, v19
	s_andn2_b64 vcc, exec, s[0:1]
	s_mov_b64 s[0:1], -1
	s_waitcnt vmcnt(1)
	v_lshlrev_b32_e32 v16, 16, v8
	v_and_b32_e32 v17, 0xffff0000, v8
	s_waitcnt vmcnt(0)
	v_lshlrev_b32_e32 v18, 16, v12
	v_and_b32_e32 v19, 0xffff0000, v12
	v_lshlrev_b32_e32 v8, 16, v9
	v_and_b32_e32 v9, 0xffff0000, v9
	v_lshlrev_b32_e32 v12, 16, v13
	v_and_b32_e32 v13, 0xffff0000, v13
	v_lshlrev_b32_e32 v20, 16, v10
	v_and_b32_e32 v21, 0xffff0000, v10
	v_lshlrev_b32_e32 v22, 16, v14
	v_and_b32_e32 v23, 0xffff0000, v14
	v_lshlrev_b32_e32 v10, 16, v11
	v_and_b32_e32 v11, 0xffff0000, v11
	v_lshlrev_b32_e32 v14, 16, v15
	v_and_b32_e32 v15, 0xffff0000, v15
	v_pk_fma_f32 v[0:1], v[0:1], v[18:19], v[16:17]
	v_pk_fma_f32 v[2:3], v[2:3], v[12:13], v[8:9]
	v_pk_fma_f32 v[4:5], v[4:5], v[22:23], v[20:21]
	v_pk_fma_f32 v[6:7], v[6:7], v[14:15], v[10:11]
	global_store_dwordx4 v[40:41], v[0:3], off offset:128
	global_store_dwordx4 v[40:41], v[4:7], off offset:144
	s_cbranch_vccnz .LBB0_466
	s_andn2_b64 vcc, exec, s[4:5]
	s_cbranch_vccnz .LBB0_465
	s_barrier
	s_branch .LBB0_465
